# v32 + FF1 HID stores write-through (sc1) so they do not occupy the XCD L2 during FF1's K-loops
# speedup vs baseline: 1.0062x; 1.0062x over previous
.LBB0_571:
	v_mov_b32_e32 v161, v164
	v_mov_b32_e32 v128, v165
	s_lshl_b32 s17, s72, 8
	s_or_b32 s17, s17, s66
	v_lshlrev_b32_e32 v160, 3, v128
	v_add_u32_e32 v128, s17, v160
	s_lshl_b32 s17, s26, 8
	s_and_b32 s28, s17, 0xfffff000
	s_ashr_i32 s29, s28, 31
	s_lshl_b64 s[28:29], s[28:29], 2
	s_add_u32 s28, s59, s28
	s_addc_u32 s29, s61, s29
	v_ashrrev_i32_e32 v129, 31, v128
	v_lshl_add_u64 v[128:129], v[128:129], 2, s[28:29]
	global_load_dwordx4 v[140:143], v[128:129], off
	global_load_dwordx4 v[136:139], v[128:129], off offset:16
	global_load_dwordx4 v[132:135], v[128:129], off offset:512
	s_nop 0
	global_load_dwordx4 v[128:131], v[128:129], off offset:528
	v_add_u32_e32 v162, s57, v161
	v_lshl_add_u32 v170, v162, 2, 0
	s_lshl_b32 s17, s72, 3
	v_add_u32_e32 v170, 0x22400, v170
	s_or_b32 s28, s17, s56
	s_ashr_i32 s27, s26, 31
	ds_read2_b32 v[172:173], v170 offset1:16
	s_ashr_i32 s29, s28, 31
	s_lshl_b64 s[26:27], s[26:27], 21
	s_lshl_b64 s[28:29], s[28:29], 14
	s_add_u32 s17, s64, s26
	s_addc_u32 s19, s65, s27
	v_ashrrev_i32_e32 v163, 31, v162
	s_add_u32 s26, s17, s28
	v_lshlrev_b64 v[162:163], 6, v[162:163]
	s_addc_u32 s27, s19, s29
	v_ashrrev_i32_e32 v161, 31, v160
	v_lshl_add_u64 v[162:163], s[26:27], 0, v[162:163]
	s_waitcnt lgkmcnt(0)
	v_mov_b32_e32 v174, v173
	v_lshl_add_u64 v[160:161], v[160:161], 1, v[162:163]
	v_add_co_u32_e32 v162, vcc, s49, v160
	s_waitcnt vmcnt(0)
	v_pk_fma_f32 v[126:127], v[126:127], v[172:173], v[142:143] op_sel_hi:[1,0,1]
	v_pk_fma_f32 v[124:125], v[124:125], v[172:173], v[140:141] op_sel_hi:[1,0,1]
	v_pk_fma_f32 v[122:123], v[122:123], v[172:173], v[138:139] op_sel_hi:[1,0,1]
	v_pk_fma_f32 v[120:121], v[120:121], v[172:173], v[136:137] op_sel_hi:[1,0,1]
	v_pk_fma_f32 v[110:111], v[110:111], v[172:173], v[134:135] op_sel_hi:[1,0,1]
	v_pk_fma_f32 v[108:109], v[108:109], v[172:173], v[132:133] op_sel_hi:[1,0,1]
	v_pk_fma_f32 v[106:107], v[106:107], v[172:173], v[130:131] op_sel_hi:[1,0,1]
	v_pk_fma_f32 v[104:105], v[104:105], v[172:173], v[128:129] op_sel_hi:[1,0,1]
	v_max_f32_e32 v124, 0, v124
	v_max_f32_e32 v120, 0, v120
	v_max_f32_e32 v125, 0, v125
	v_max_f32_e32 v121, 0, v121
	v_max_f32_e32 v126, 0, v126
	v_max_f32_e32 v122, 0, v122
	v_max_f32_e32 v127, 0, v127
	v_max_f32_e32 v123, 0, v123
	v_max_f32_e32 v108, 0, v108
	v_max_f32_e32 v104, 0, v104
	v_max_f32_e32 v109, 0, v109
	v_max_f32_e32 v105, 0, v105
	v_max_f32_e32 v110, 0, v110
	v_max_f32_e32 v106, 0, v106
	v_max_f32_e32 v111, 0, v111
	v_max_f32_e32 v107, 0, v107
	v_pk_mul_f32 v[124:125], v[124:125], v[124:125]
	v_pk_mul_f32 v[120:121], v[120:121], v[120:121]
	v_pk_mul_f32 v[126:127], v[126:127], v[126:127]
	v_pk_mul_f32 v[122:123], v[122:123], v[122:123]
	v_pk_mul_f32 v[108:109], v[108:109], v[108:109]
	v_pk_mul_f32 v[172:173], v[104:105], v[104:105]
	v_pk_mul_f32 v[110:111], v[110:111], v[110:111]
	v_pk_mul_f32 v[176:177], v[106:107], v[106:107]
	v_pk_fma_f32 v[118:119], v[118:119], v[174:175], v[142:143] op_sel_hi:[1,0,1]
	v_pk_fma_f32 v[116:117], v[116:117], v[174:175], v[140:141] op_sel_hi:[1,0,1]
	v_pk_fma_f32 v[114:115], v[114:115], v[174:175], v[138:139] op_sel_hi:[1,0,1]
	v_pk_fma_f32 v[112:113], v[112:113], v[174:175], v[136:137] op_sel_hi:[1,0,1]
	v_cvt_pk_bf16_f32 v104, v124, v125
	v_cvt_pk_bf16_f32 v105, v126, v127
	v_cvt_pk_bf16_f32 v106, v120, v121
	v_cvt_pk_bf16_f32 v107, v122, v123
	v_cvt_pk_bf16_f32 v108, v108, v109
	v_cvt_pk_bf16_f32 v109, v110, v111
	v_cvt_pk_bf16_f32 v110, v172, v173
	v_cvt_pk_bf16_f32 v111, v176, v177
	v_addc_co_u32_e32 v163, vcc, 0, v161, vcc
	v_max_f32_e32 v116, 0, v116
	v_max_f32_e32 v112, 0, v112
	v_max_f32_e32 v117, 0, v117
	global_store_dwordx4 v[160:161], v[104:107], off sc1
	global_store_dwordx4 v[162:163], v[108:111], off sc1
	v_max_f32_e32 v113, 0, v113
	v_pk_mul_f32 v[104:105], v[116:117], v[116:117]
	v_max_f32_e32 v108, 0, v118
	v_max_f32_e32 v110, 0, v114
	v_max_f32_e32 v109, 0, v119
	v_max_f32_e32 v111, 0, v115
	v_pk_mul_f32 v[106:107], v[112:113], v[112:113]
	v_pk_mul_f32 v[108:109], v[108:109], v[108:109]
	v_pk_mul_f32 v[110:111], v[110:111], v[110:111]
	v_pk_fma_f32 v[100:101], v[100:101], v[174:175], v[132:133] op_sel_hi:[1,0,1]
	v_pk_fma_f32 v[96:97], v[96:97], v[174:175], v[128:129] op_sel_hi:[1,0,1]
	v_cvt_pk_bf16_f32 v104, v104, v105
	v_cvt_pk_bf16_f32 v105, v108, v109
	v_cvt_pk_bf16_f32 v106, v106, v107
	v_cvt_pk_bf16_f32 v107, v110, v111
	v_pk_fma_f32 v[102:103], v[102:103], v[174:175], v[134:135] op_sel_hi:[1,0,1]
	v_max_f32_e32 v100, 0, v100
	v_max_f32_e32 v96, 0, v96
	v_max_f32_e32 v101, 0, v101
	v_max_f32_e32 v97, 0, v97
	global_store_dwordx4 v[160:161], v[104:107], off offset:1024 sc1
	v_pk_mul_f32 v[100:101], v[100:101], v[100:101]
	v_pk_fma_f32 v[98:99], v[98:99], v[174:175], v[130:131] op_sel_hi:[1,0,1]
	v_pk_mul_f32 v[104:105], v[96:97], v[96:97]
	v_max_f32_e32 v96, 0, v102
	v_max_f32_e32 v97, 0, v103
	v_pk_mul_f32 v[102:103], v[96:97], v[96:97]
	v_cvt_pk_bf16_f32 v96, v100, v101
	ds_read2_b32 v[100:101], v170 offset0:32 offset1:48
	v_max_f32_e32 v98, 0, v98
	v_max_f32_e32 v99, 0, v99
	v_pk_mul_f32 v[106:107], v[98:99], v[98:99]
	v_cvt_pk_bf16_f32 v97, v102, v103
	s_waitcnt lgkmcnt(0)
	v_pk_fma_f32 v[88:89], v[88:89], v[100:101], v[136:137] op_sel_hi:[1,0,1]
	v_cvt_pk_bf16_f32 v98, v104, v105
	v_cvt_pk_bf16_f32 v99, v106, v107
	v_pk_fma_f32 v[94:95], v[94:95], v[100:101], v[142:143] op_sel_hi:[1,0,1]
	v_pk_fma_f32 v[92:93], v[92:93], v[100:101], v[140:141] op_sel_hi:[1,0,1]
	v_pk_fma_f32 v[90:91], v[90:91], v[100:101], v[138:139] op_sel_hi:[1,0,1]
	v_max_f32_e32 v88, 0, v88
	v_max_f32_e32 v89, 0, v89
	global_store_dwordx4 v[162:163], v[96:99], off offset:1024 sc1
	v_max_f32_e32 v92, 0, v92
	v_max_f32_e32 v93, 0, v93
	v_pk_mul_f32 v[96:97], v[88:89], v[88:89]
	v_max_f32_e32 v88, 0, v94
	v_max_f32_e32 v90, 0, v90
	v_max_f32_e32 v89, 0, v95
	v_max_f32_e32 v91, 0, v91
	v_pk_mul_f32 v[92:93], v[92:93], v[92:93]
	v_pk_mul_f32 v[94:95], v[88:89], v[88:89]
	v_pk_mul_f32 v[98:99], v[90:91], v[90:91]
	v_pk_fma_f32 v[80:81], v[80:81], v[100:101], v[128:129] op_sel_hi:[1,0,1]
	v_cvt_pk_bf16_f32 v88, v92, v93
	v_cvt_pk_bf16_f32 v89, v94, v95
	v_cvt_pk_bf16_f32 v90, v96, v97
	v_cvt_pk_bf16_f32 v91, v98, v99
	v_pk_fma_f32 v[86:87], v[86:87], v[100:101], v[134:135] op_sel_hi:[1,0,1]
	v_pk_fma_f32 v[84:85], v[84:85], v[100:101], v[132:133] op_sel_hi:[1,0,1]
	v_pk_fma_f32 v[82:83], v[82:83], v[100:101], v[130:131] op_sel_hi:[1,0,1]
	v_max_f32_e32 v80, 0, v80
	v_max_f32_e32 v81, 0, v81
	global_store_dwordx4 v[160:161], v[88:91], off offset:2048 sc1
	v_max_f32_e32 v84, 0, v84
	v_max_f32_e32 v85, 0, v85
	v_pk_mul_f32 v[88:89], v[80:81], v[80:81]
	v_max_f32_e32 v80, 0, v86
	v_max_f32_e32 v82, 0, v82
	v_max_f32_e32 v81, 0, v87
	v_max_f32_e32 v83, 0, v83
	v_pk_mul_f32 v[84:85], v[84:85], v[84:85]
	v_pk_mul_f32 v[86:87], v[80:81], v[80:81]
	v_pk_mul_f32 v[90:91], v[82:83], v[82:83]
	v_cvt_pk_bf16_f32 v80, v84, v85
	v_cvt_pk_bf16_f32 v81, v86, v87
	v_cvt_pk_bf16_f32 v82, v88, v89
	v_cvt_pk_bf16_f32 v83, v90, v91
	global_store_dwordx4 v[162:163], v[80:83], off offset:2048 sc1
	s_nop 1
	v_mov_b32_e32 v80, v101
	v_pk_fma_f32 v[72:73], v[72:73], v[80:81], v[136:137] op_sel_hi:[1,0,1]
	v_pk_fma_f32 v[78:79], v[78:79], v[80:81], v[142:143] op_sel_hi:[1,0,1]
	v_pk_fma_f32 v[76:77], v[76:77], v[80:81], v[140:141] op_sel_hi:[1,0,1]
	v_pk_fma_f32 v[74:75], v[74:75], v[80:81], v[138:139] op_sel_hi:[1,0,1]
	v_max_f32_e32 v72, 0, v72
	v_max_f32_e32 v73, 0, v73
	v_max_f32_e32 v76, 0, v76
	v_max_f32_e32 v77, 0, v77
	v_pk_mul_f32 v[82:83], v[72:73], v[72:73]
	v_max_f32_e32 v72, 0, v78
	v_max_f32_e32 v74, 0, v74
	v_max_f32_e32 v73, 0, v79
	v_max_f32_e32 v75, 0, v75
	v_pk_mul_f32 v[76:77], v[76:77], v[76:77]
	v_pk_mul_f32 v[78:79], v[72:73], v[72:73]
	v_pk_mul_f32 v[84:85], v[74:75], v[74:75]
	v_pk_fma_f32 v[68:69], v[68:69], v[80:81], v[132:133] op_sel_hi:[1,0,1]
	v_pk_fma_f32 v[64:65], v[64:65], v[80:81], v[128:129] op_sel_hi:[1,0,1]
	v_cvt_pk_bf16_f32 v72, v76, v77
	v_cvt_pk_bf16_f32 v73, v78, v79
	v_cvt_pk_bf16_f32 v74, v82, v83
	v_cvt_pk_bf16_f32 v75, v84, v85
	v_pk_fma_f32 v[70:71], v[70:71], v[80:81], v[134:135] op_sel_hi:[1,0,1]
	v_max_f32_e32 v68, 0, v68
	v_max_f32_e32 v64, 0, v64
	v_max_f32_e32 v69, 0, v69
	v_max_f32_e32 v65, 0, v65
	global_store_dwordx4 v[160:161], v[72:75], off offset:3072 sc1
	v_pk_mul_f32 v[68:69], v[68:69], v[68:69]
	v_pk_fma_f32 v[66:67], v[66:67], v[80:81], v[130:131] op_sel_hi:[1,0,1]
	v_pk_mul_f32 v[72:73], v[64:65], v[64:65]
	v_max_f32_e32 v64, 0, v70
	v_max_f32_e32 v65, 0, v71
	v_pk_mul_f32 v[70:71], v[64:65], v[64:65]
	v_cvt_pk_bf16_f32 v64, v68, v69
	ds_read2_b32 v[68:69], v170 offset0:128 offset1:144
	v_max_f32_e32 v66, 0, v66
	v_max_f32_e32 v67, 0, v67
	v_pk_mul_f32 v[74:75], v[66:67], v[66:67]
	v_cvt_pk_bf16_f32 v65, v70, v71
	s_waitcnt lgkmcnt(0)
	v_pk_fma_f32 v[60:61], v[60:61], v[68:69], v[140:141] op_sel_hi:[1,0,1]
	v_pk_fma_f32 v[56:57], v[56:57], v[68:69], v[136:137] op_sel_hi:[1,0,1]
	v_cvt_pk_bf16_f32 v66, v72, v73
	v_cvt_pk_bf16_f32 v67, v74, v75
	v_pk_fma_f32 v[62:63], v[62:63], v[68:69], v[142:143] op_sel_hi:[1,0,1]
	v_pk_fma_f32 v[58:59], v[58:59], v[68:69], v[138:139] op_sel_hi:[1,0,1]
	v_max_f32_e32 v60, 0, v60
	v_max_f32_e32 v56, 0, v56
	v_max_f32_e32 v61, 0, v61
	v_max_f32_e32 v57, 0, v57
	global_store_dwordx4 v[162:163], v[64:67], off offset:3072 sc1
	v_pk_mul_f32 v[60:61], v[60:61], v[60:61]
	v_max_f32_e32 v58, 0, v58
	v_pk_mul_f32 v[64:65], v[56:57], v[56:57]
	v_max_f32_e32 v56, 0, v62
	v_max_f32_e32 v57, 0, v63
	v_max_f32_e32 v59, 0, v59
	v_pk_mul_f32 v[62:63], v[56:57], v[56:57]
	v_pk_mul_f32 v[66:67], v[58:59], v[58:59]
	v_cvt_pk_bf16_f32 v56, v60, v61
	v_add_co_u32_e32 v60, vcc, s51, v160
	v_pk_fma_f32 v[52:53], v[52:53], v[68:69], v[132:133] op_sel_hi:[1,0,1]
	v_pk_fma_f32 v[48:49], v[48:49], v[68:69], v[128:129] op_sel_hi:[1,0,1]
	v_cvt_pk_bf16_f32 v57, v62, v63
	v_cvt_pk_bf16_f32 v58, v64, v65
	v_cvt_pk_bf16_f32 v59, v66, v67
	v_addc_co_u32_e32 v61, vcc, 0, v161, vcc
	v_pk_fma_f32 v[54:55], v[54:55], v[68:69], v[134:135] op_sel_hi:[1,0,1]
	v_pk_fma_f32 v[50:51], v[50:51], v[68:69], v[130:131] op_sel_hi:[1,0,1]
	v_max_f32_e32 v52, 0, v52
	v_max_f32_e32 v48, 0, v48
	v_max_f32_e32 v53, 0, v53
	v_max_f32_e32 v49, 0, v49
	global_store_dwordx4 v[60:61], v[56:59], off sc1
	v_pk_mul_f32 v[52:53], v[52:53], v[52:53]
	v_max_f32_e32 v50, 0, v50
	v_pk_mul_f32 v[56:57], v[48:49], v[48:49]
	v_max_f32_e32 v48, 0, v54
	v_max_f32_e32 v49, 0, v55
	v_max_f32_e32 v51, 0, v51
	v_pk_mul_f32 v[54:55], v[48:49], v[48:49]
	v_pk_mul_f32 v[58:59], v[50:51], v[50:51]
	v_cvt_pk_bf16_f32 v48, v52, v53
	v_add_co_u32_e32 v52, vcc, s50, v160
	v_cvt_pk_bf16_f32 v49, v54, v55
	v_cvt_pk_bf16_f32 v50, v56, v57
	v_cvt_pk_bf16_f32 v51, v58, v59
	v_addc_co_u32_e32 v53, vcc, 0, v161, vcc
	global_store_dwordx4 v[52:53], v[48:51], off sc1
	s_andn2_b64 vcc, exec, s[4:5]
	s_mov_b64 s[4:5], -1
	v_mov_b32_e32 v48, v69
	v_pk_fma_f32 v[40:41], v[40:41], v[48:49], v[136:137] op_sel_hi:[1,0,1]
	v_pk_fma_f32 v[46:47], v[46:47], v[48:49], v[142:143] op_sel_hi:[1,0,1]
	v_pk_fma_f32 v[44:45], v[44:45], v[48:49], v[140:141] op_sel_hi:[1,0,1]
	v_pk_fma_f32 v[42:43], v[42:43], v[48:49], v[138:139] op_sel_hi:[1,0,1]
	v_max_f32_e32 v40, 0, v40
	v_max_f32_e32 v41, 0, v41
	v_max_f32_e32 v44, 0, v44
	v_max_f32_e32 v45, 0, v45
	v_pk_mul_f32 v[50:51], v[40:41], v[40:41]
	v_max_f32_e32 v40, 0, v46
	v_max_f32_e32 v42, 0, v42
	v_max_f32_e32 v41, 0, v47
	v_max_f32_e32 v43, 0, v43
	v_pk_mul_f32 v[44:45], v[44:45], v[44:45]
	v_pk_mul_f32 v[46:47], v[40:41], v[40:41]
	v_pk_mul_f32 v[54:55], v[42:43], v[42:43]
	v_pk_fma_f32 v[36:37], v[36:37], v[48:49], v[132:133] op_sel_hi:[1,0,1]
	v_pk_fma_f32 v[32:33], v[32:33], v[48:49], v[128:129] op_sel_hi:[1,0,1]
	v_cvt_pk_bf16_f32 v40, v44, v45
	v_cvt_pk_bf16_f32 v41, v46, v47
	v_cvt_pk_bf16_f32 v42, v50, v51
	v_cvt_pk_bf16_f32 v43, v54, v55
	v_pk_fma_f32 v[38:39], v[38:39], v[48:49], v[134:135] op_sel_hi:[1,0,1]
	v_max_f32_e32 v36, 0, v36
	v_max_f32_e32 v32, 0, v32
	v_max_f32_e32 v37, 0, v37
	v_max_f32_e32 v33, 0, v33
	global_store_dwordx4 v[60:61], v[40:43], off offset:1024 sc1
	v_pk_mul_f32 v[36:37], v[36:37], v[36:37]
	v_pk_fma_f32 v[34:35], v[34:35], v[48:49], v[130:131] op_sel_hi:[1,0,1]
	v_pk_mul_f32 v[40:41], v[32:33], v[32:33]
	v_max_f32_e32 v32, 0, v38
	v_max_f32_e32 v33, 0, v39
	v_pk_mul_f32 v[38:39], v[32:33], v[32:33]
	v_cvt_pk_bf16_f32 v32, v36, v37
	ds_read2_b32 v[36:37], v170 offset0:160 offset1:176
	v_max_f32_e32 v34, 0, v34
	v_max_f32_e32 v35, 0, v35
	v_pk_mul_f32 v[42:43], v[34:35], v[34:35]
	v_cvt_pk_bf16_f32 v33, v38, v39
	s_waitcnt lgkmcnt(0)
	v_pk_fma_f32 v[24:25], v[24:25], v[36:37], v[136:137] op_sel_hi:[1,0,1]
	v_cvt_pk_bf16_f32 v34, v40, v41
	v_cvt_pk_bf16_f32 v35, v42, v43
	v_pk_fma_f32 v[30:31], v[30:31], v[36:37], v[142:143] op_sel_hi:[1,0,1]
	v_pk_fma_f32 v[28:29], v[28:29], v[36:37], v[140:141] op_sel_hi:[1,0,1]
	v_pk_fma_f32 v[26:27], v[26:27], v[36:37], v[138:139] op_sel_hi:[1,0,1]
	v_max_f32_e32 v24, 0, v24
	v_max_f32_e32 v25, 0, v25
	global_store_dwordx4 v[52:53], v[32:35], off offset:1024 sc1
	v_max_f32_e32 v28, 0, v28
	v_max_f32_e32 v29, 0, v29
	v_pk_mul_f32 v[32:33], v[24:25], v[24:25]
	v_max_f32_e32 v24, 0, v30
	v_max_f32_e32 v26, 0, v26
	v_max_f32_e32 v25, 0, v31
	v_max_f32_e32 v27, 0, v27
	v_pk_mul_f32 v[28:29], v[28:29], v[28:29]
	v_pk_mul_f32 v[30:31], v[24:25], v[24:25]
	v_pk_mul_f32 v[34:35], v[26:27], v[26:27]
	v_pk_fma_f32 v[16:17], v[16:17], v[36:37], v[128:129] op_sel_hi:[1,0,1]
	v_cvt_pk_bf16_f32 v24, v28, v29
	v_cvt_pk_bf16_f32 v25, v30, v31
	v_cvt_pk_bf16_f32 v26, v32, v33
	v_cvt_pk_bf16_f32 v27, v34, v35
	v_pk_fma_f32 v[22:23], v[22:23], v[36:37], v[134:135] op_sel_hi:[1,0,1]
	v_pk_fma_f32 v[20:21], v[20:21], v[36:37], v[132:133] op_sel_hi:[1,0,1]
	v_pk_fma_f32 v[18:19], v[18:19], v[36:37], v[130:131] op_sel_hi:[1,0,1]
	v_max_f32_e32 v16, 0, v16
	v_max_f32_e32 v17, 0, v17
	global_store_dwordx4 v[60:61], v[24:27], off offset:2048 sc1
	v_max_f32_e32 v20, 0, v20
	v_max_f32_e32 v21, 0, v21
	v_pk_mul_f32 v[24:25], v[16:17], v[16:17]
	v_max_f32_e32 v16, 0, v22
	v_max_f32_e32 v18, 0, v18
	v_max_f32_e32 v17, 0, v23
	v_max_f32_e32 v19, 0, v19
	v_pk_mul_f32 v[20:21], v[20:21], v[20:21]
	v_pk_mul_f32 v[22:23], v[16:17], v[16:17]
	v_pk_mul_f32 v[26:27], v[18:19], v[18:19]
	v_cvt_pk_bf16_f32 v16, v20, v21
	v_cvt_pk_bf16_f32 v17, v22, v23
	v_cvt_pk_bf16_f32 v18, v24, v25
	v_cvt_pk_bf16_f32 v19, v26, v27
	global_store_dwordx4 v[52:53], v[16:19], off offset:2048 sc1
	s_nop 1
	v_mov_b32_e32 v16, v37
	v_pk_fma_f32 v[8:9], v[8:9], v[16:17], v[136:137] op_sel_hi:[1,0,1]
	v_pk_fma_f32 v[14:15], v[14:15], v[16:17], v[142:143] op_sel_hi:[1,0,1]
	v_pk_fma_f32 v[12:13], v[12:13], v[16:17], v[140:141] op_sel_hi:[1,0,1]
	v_pk_fma_f32 v[10:11], v[10:11], v[16:17], v[138:139] op_sel_hi:[1,0,1]
	v_max_f32_e32 v8, 0, v8
	v_max_f32_e32 v9, 0, v9
	v_max_f32_e32 v12, 0, v12
	v_max_f32_e32 v13, 0, v13
	v_pk_mul_f32 v[18:19], v[8:9], v[8:9]
	v_max_f32_e32 v8, 0, v14
	v_max_f32_e32 v10, 0, v10
	v_max_f32_e32 v9, 0, v15
	v_max_f32_e32 v11, 0, v11
	v_pk_mul_f32 v[12:13], v[12:13], v[12:13]
	v_pk_mul_f32 v[14:15], v[8:9], v[8:9]
	v_pk_mul_f32 v[20:21], v[10:11], v[10:11]
	v_pk_fma_f32 v[0:1], v[0:1], v[16:17], v[128:129] op_sel_hi:[1,0,1]
	v_cvt_pk_bf16_f32 v8, v12, v13
	v_cvt_pk_bf16_f32 v9, v14, v15
	v_cvt_pk_bf16_f32 v10, v18, v19
	v_cvt_pk_bf16_f32 v11, v20, v21
	v_pk_fma_f32 v[6:7], v[6:7], v[16:17], v[134:135] op_sel_hi:[1,0,1]
	v_pk_fma_f32 v[4:5], v[4:5], v[16:17], v[132:133] op_sel_hi:[1,0,1]
	v_pk_fma_f32 v[2:3], v[2:3], v[16:17], v[130:131] op_sel_hi:[1,0,1]
	v_max_f32_e32 v0, 0, v0
	v_max_f32_e32 v1, 0, v1
	global_store_dwordx4 v[60:61], v[8:11], off offset:3072 sc1
	v_max_f32_e32 v4, 0, v4
	v_max_f32_e32 v5, 0, v5
	v_pk_mul_f32 v[8:9], v[0:1], v[0:1]
	v_max_f32_e32 v0, 0, v6
	v_max_f32_e32 v2, 0, v2
	v_max_f32_e32 v1, 0, v7
	v_max_f32_e32 v3, 0, v3
	v_pk_mul_f32 v[4:5], v[4:5], v[4:5]
	v_pk_mul_f32 v[6:7], v[0:1], v[0:1]
	v_pk_mul_f32 v[10:11], v[2:3], v[2:3]
	v_cvt_pk_bf16_f32 v0, v4, v5
	v_cvt_pk_bf16_f32 v1, v6, v7
	v_cvt_pk_bf16_f32 v2, v8, v9
	v_cvt_pk_bf16_f32 v3, v10, v11
	global_store_dwordx4 v[52:53], v[0:3], off offset:3072 sc1
	s_cbranch_vccnz .LBB0_560
	s_andn2_b64 vcc, exec, s[8:9]
	s_cbranch_vccnz .LBB0_559
	s_barrier
	s_branch .LBB0_559
